# grid barrier: waiting WGs spin on the top-level generation word directly; per-XCD generation bump dropped (one round trip less on the release path)
# baseline (speedup 1.0000x reference)
; __device__ __forceinline__ unsigned xb_ld(unsigned* p)              { return __hip_atomic_load(p, __ATOMIC_RELAXED, __HIP_MEMORY_SCOPE_AGENT); }
; __device__ __forceinline__ unsigned xb_add(unsigned* p, unsigned v) { return __hip_atomic_fetch_add(p, v, __ATOMIC_RELAXED, __HIP_MEMORY_SCOPE_AGENT); }
; #define XB_SPIN(cond, bar) do { unsigned _sp = 0; while (cond) { __builtin_amdgcn_s_sleep(1); \
;     if ((++_sp & 255u) == 0u) { if (xb_ld(&(bar)[XB_TMO])) break; if (_sp > XB_SPIN_CAP) { atomicAdd(&(bar)[XB_TMO], 1u); break; } } } } while (0)
; __device__ __forceinline__ void xcd_barrier(const XcdBarrier& b) {
;     ...
;         const unsigned old = xb_add(&bar[XB_XSUB(b.x)], 1u);
;         const unsigned gen = old / nloc;
;         if (old + 1u == (gen + 1u) * nloc) {
;             __builtin_amdgcn_fence(__ATOMIC_RELEASE, "agent");
;             asm volatile("s_waitcnt vmcnt(0)" ::: "memory");
;             const unsigned og = xb_add(&bar[XB_TOP], 1u);
;             const unsigned tg = og / nx;
;             if (og + 1u == (tg + 1u) * nx) xb_add(&bar[XB_TOPGEN], 1u);
;             else XB_SPIN(xb_ld(&bar[XB_TOPGEN]) == tg, bar);
;             __builtin_amdgcn_fence(__ATOMIC_ACQUIRE, "agent");
;             xb_add(&bar[XB_XGEN(b.x)], 1u);
;             asm volatile("s_waitcnt vmcnt(0)" ::: "memory");
;         } else {
;             XB_SPIN(xb_ld(&bar[XB_XGEN(b.x)]) == gen, bar);
.LBB0_119:
	s_or_b64 exec, exec, s[12:13]
	v_cvt_f32_u32_e32 v4, v2
	s_waitcnt vmcnt(0)
	v_readfirstlane_b32 s3, v3
	v_sub_u32_e32 v3, 0, v2
	v_rcp_iflag_f32_e32 v4, v4
	v_add_u32_e32 v5, s3, v1
	v_mul_f32_e32 v4, 0x4f7ffffe, v4
	v_cvt_u32_f32_e32 v4, v4
	v_mul_lo_u32 v1, v3, v4
	v_mul_hi_u32 v1, v4, v1
	v_add_u32_e32 v1, v4, v1
	v_mul_hi_u32 v1, v5, v1
	v_mul_lo_u32 v3, v1, v2
	v_sub_u32_e32 v3, v5, v3
	v_add_u32_e32 v4, 1, v1
	v_cmp_ge_u32_e32 vcc, v3, v2
	s_nop 1
	v_cndmask_b32_e32 v1, v1, v4, vcc
	v_sub_u32_e32 v4, v3, v2
	v_cndmask_b32_e32 v3, v3, v4, vcc
	v_add_u32_e32 v4, 1, v1
	v_cmp_ge_u32_e32 vcc, v3, v2
	v_add_u32_e32 v3, 1, v5
	s_nop 0
	v_cndmask_b32_e32 v1, v1, v4, vcc
	v_mul_lo_u32 v4, v2, v1
	v_add_u32_e32 v2, v4, v2
	v_cmp_ne_u32_e32 vcc, v3, v2
	s_and_saveexec_b64 s[10:11], vcc
	s_xor_b64 s[10:11], exec, s[10:11]
	s_cbranch_execz .LBB0_133
	s_waitcnt lgkmcnt(0)
	v_readlane_b32 s14, v254, 39
	v_readlane_b32 s15, v254, 40
	s_nop 4
	global_load_dword v0, v193, s[14:15] sc1
	s_waitcnt vmcnt(0)
	v_cmp_eq_u32_e32 vcc, v0, v1
	s_and_saveexec_b64 s[12:13], vcc
	s_cbranch_execz .LBB0_132
	s_mov_b32 s3, 1
	s_mov_b64 s[16:17], 0
	s_branch .LBB0_123

; __device__ __forceinline__ unsigned xb_add(unsigned* p, unsigned v) { return __hip_atomic_fetch_add(p, v, __ATOMIC_RELAXED, __HIP_MEMORY_SCOPE_AGENT); }
; __device__ __forceinline__ void xcd_barrier(const XcdBarrier& b) {
;     ...
;             __builtin_amdgcn_fence(__ATOMIC_ACQUIRE, "agent");
;             xb_add(&bar[XB_XGEN(b.x)], 1u);
;             asm volatile("s_waitcnt vmcnt(0)" ::: "memory");
.LBB0_150:
	s_or_b64 exec, exec, s[10:11]
	s_mov_b64 s[10:11], exec
	v_mbcnt_lo_u32_b32 v0, s10, 0
	v_mbcnt_hi_u32_b32 v0, s11, v0
	v_cmp_eq_u32_e32 vcc, 0, v0
	s_waitcnt vmcnt(0)
	buffer_inv sc1
	s_and_saveexec_b64 s[12:13], vcc
	s_cbranch_execz .LBB0_152
	s_bcnt1_i32_b64 s3, s[10:11]
	v_mov_b32_e32 v0, s3
.LBB0_152:
	s_or_b64 exec, exec, s[12:13]
	s_waitcnt vmcnt(0)

; __device__ __forceinline__ unsigned xb_ld(unsigned* p)              { return __hip_atomic_load(p, __ATOMIC_RELAXED, __HIP_MEMORY_SCOPE_AGENT); }
; __device__ __forceinline__ unsigned xb_add(unsigned* p, unsigned v) { return __hip_atomic_fetch_add(p, v, __ATOMIC_RELAXED, __HIP_MEMORY_SCOPE_AGENT); }
; #define XB_SPIN(cond, bar) do { unsigned _sp = 0; while (cond) { __builtin_amdgcn_s_sleep(1); \
;     if ((++_sp & 255u) == 0u) { if (xb_ld(&(bar)[XB_TMO])) break; if (_sp > XB_SPIN_CAP) { atomicAdd(&(bar)[XB_TMO], 1u); break; } } } } while (0)
; __device__ __forceinline__ void xcd_barrier(const XcdBarrier& b) {
;     ...
;         const unsigned old = xb_add(&bar[XB_XSUB(b.x)], 1u);
;         const unsigned gen = old / nloc;
;         if (old + 1u == (gen + 1u) * nloc) {
;             __builtin_amdgcn_fence(__ATOMIC_RELEASE, "agent");
;             asm volatile("s_waitcnt vmcnt(0)" ::: "memory");
;             const unsigned og = xb_add(&bar[XB_TOP], 1u);
;             const unsigned tg = og / nx;
;             if (og + 1u == (tg + 1u) * nx) xb_add(&bar[XB_TOPGEN], 1u);
;             else XB_SPIN(xb_ld(&bar[XB_TOPGEN]) == tg, bar);
;             __builtin_amdgcn_fence(__ATOMIC_ACQUIRE, "agent");
;             xb_add(&bar[XB_XGEN(b.x)], 1u);
;             asm volatile("s_waitcnt vmcnt(0)" ::: "memory");
;         } else {
;             XB_SPIN(xb_ld(&bar[XB_XGEN(b.x)]) == gen, bar);
.LBB0_271:
	s_or_b64 exec, exec, s[10:11]
	v_cvt_f32_u32_e32 v4, v2
	s_waitcnt vmcnt(0)
	v_readfirstlane_b32 s3, v3
	v_sub_u32_e32 v3, 0, v2
	v_rcp_iflag_f32_e32 v4, v4
	v_add_u32_e32 v5, s3, v1
	v_mul_f32_e32 v4, 0x4f7ffffe, v4
	v_cvt_u32_f32_e32 v4, v4
	v_mul_lo_u32 v1, v3, v4
	v_mul_hi_u32 v1, v4, v1
	v_add_u32_e32 v1, v4, v1
	v_mul_hi_u32 v1, v5, v1
	v_mul_lo_u32 v3, v1, v2
	v_sub_u32_e32 v3, v5, v3
	v_add_u32_e32 v4, 1, v1
	v_cmp_ge_u32_e32 vcc, v3, v2
	s_nop 1
	v_cndmask_b32_e32 v1, v1, v4, vcc
	v_sub_u32_e32 v4, v3, v2
	v_cndmask_b32_e32 v3, v3, v4, vcc
	v_add_u32_e32 v4, 1, v1
	v_cmp_ge_u32_e32 vcc, v3, v2
	v_add_u32_e32 v3, 1, v5
	s_nop 0
	v_cndmask_b32_e32 v1, v1, v4, vcc
	v_mul_lo_u32 v4, v2, v1
	v_add_u32_e32 v2, v4, v2
	v_cmp_ne_u32_e32 vcc, v3, v2
	s_and_saveexec_b64 s[8:9], vcc
	s_xor_b64 s[8:9], exec, s[8:9]
	s_cbranch_execz .LBB0_285
	s_waitcnt lgkmcnt(0)
	v_readlane_b32 s12, v254, 39
	v_readlane_b32 s13, v254, 40
	s_nop 4
	global_load_dword v0, v193, s[12:13] sc1
	s_waitcnt vmcnt(0)
	v_cmp_eq_u32_e32 vcc, v0, v1
	s_and_saveexec_b64 s[10:11], vcc
	s_cbranch_execz .LBB0_284
	s_mov_b32 s3, 1
	s_mov_b64 s[14:15], 0
	s_branch .LBB0_275

; __device__ __forceinline__ unsigned xb_add(unsigned* p, unsigned v) { return __hip_atomic_fetch_add(p, v, __ATOMIC_RELAXED, __HIP_MEMORY_SCOPE_AGENT); }
; __device__ __forceinline__ void xcd_barrier(const XcdBarrier& b) {
;     ...
;             __builtin_amdgcn_fence(__ATOMIC_ACQUIRE, "agent");
;             xb_add(&bar[XB_XGEN(b.x)], 1u);
;             asm volatile("s_waitcnt vmcnt(0)" ::: "memory");
.LBB0_302:
	s_or_b64 exec, exec, s[10:11]
	s_mov_b64 s[10:11], exec
	v_mbcnt_lo_u32_b32 v0, s10, 0
	v_mbcnt_hi_u32_b32 v0, s11, v0
	v_cmp_eq_u32_e32 vcc, 0, v0
	s_waitcnt vmcnt(0)
	buffer_inv sc1
	s_and_saveexec_b64 s[12:13], vcc
	s_cbranch_execz .LBB0_304
	s_bcnt1_i32_b64 s3, s[10:11]
	v_mov_b32_e32 v0, s3
.LBB0_304:
	s_or_b64 exec, exec, s[12:13]
	s_waitcnt vmcnt(0)

; __device__ __forceinline__ unsigned xb_add(unsigned* p, unsigned v) { return __hip_atomic_fetch_add(p, v, __ATOMIC_RELAXED, __HIP_MEMORY_SCOPE_AGENT); }
; __device__ __forceinline__ void xcd_barrier(const XcdBarrier& b) {
;     ...
;             __builtin_amdgcn_fence(__ATOMIC_ACQUIRE, "agent");
;             xb_add(&bar[XB_XGEN(b.x)], 1u);
;             asm volatile("s_waitcnt vmcnt(0)" ::: "memory");
.LBB0_429:
	s_or_b64 exec, exec, s[10:11]
	s_mov_b64 s[10:11], exec
	v_mbcnt_lo_u32_b32 v0, s10, 0
	v_mbcnt_hi_u32_b32 v0, s11, v0
	v_cmp_eq_u32_e32 vcc, 0, v0
	s_waitcnt vmcnt(0)
	buffer_inv sc1
	s_and_saveexec_b64 s[12:13], vcc
	s_cbranch_execz .LBB0_431
	s_bcnt1_i32_b64 s3, s[10:11]
	v_mov_b32_e32 v0, s3
.LBB0_431:
	s_or_b64 exec, exec, s[12:13]
	s_waitcnt vmcnt(0)

; __device__ __forceinline__ unsigned xb_ld(unsigned* p)              { return __hip_atomic_load(p, __ATOMIC_RELAXED, __HIP_MEMORY_SCOPE_AGENT); }
; __device__ __forceinline__ unsigned xb_add(unsigned* p, unsigned v) { return __hip_atomic_fetch_add(p, v, __ATOMIC_RELAXED, __HIP_MEMORY_SCOPE_AGENT); }
; #define XB_SPIN(cond, bar) do { unsigned _sp = 0; while (cond) { __builtin_amdgcn_s_sleep(1); \
;     if ((++_sp & 255u) == 0u) { if (xb_ld(&(bar)[XB_TMO])) break; if (_sp > XB_SPIN_CAP) { atomicAdd(&(bar)[XB_TMO], 1u); break; } } } } while (0)
; __device__ __forceinline__ void xcd_barrier(const XcdBarrier& b) {
;     ...
;         const unsigned old = xb_add(&bar[XB_XSUB(b.x)], 1u);
;         const unsigned gen = old / nloc;
;         if (old + 1u == (gen + 1u) * nloc) {
;             __builtin_amdgcn_fence(__ATOMIC_RELEASE, "agent");
;             asm volatile("s_waitcnt vmcnt(0)" ::: "memory");
;             const unsigned og = xb_add(&bar[XB_TOP], 1u);
;             const unsigned tg = og / nx;
;             if (og + 1u == (tg + 1u) * nx) xb_add(&bar[XB_TOPGEN], 1u);
;             else XB_SPIN(xb_ld(&bar[XB_TOPGEN]) == tg, bar);
;             __builtin_amdgcn_fence(__ATOMIC_ACQUIRE, "agent");
;             xb_add(&bar[XB_XGEN(b.x)], 1u);
;             asm volatile("s_waitcnt vmcnt(0)" ::: "memory");
;         } else {
;             XB_SPIN(xb_ld(&bar[XB_XGEN(b.x)]) == gen, bar);
.LBB0_583:
	s_or_b64 exec, exec, s[8:9]
	v_cvt_f32_u32_e32 v4, v2
	s_waitcnt vmcnt(0)
	v_readfirstlane_b32 s6, v3
	v_sub_u32_e32 v3, 0, v2
	v_rcp_iflag_f32_e32 v4, v4
	v_add_u32_e32 v5, s6, v1
	v_mul_f32_e32 v4, 0x4f7ffffe, v4
	v_cvt_u32_f32_e32 v4, v4
	v_mul_lo_u32 v1, v3, v4
	v_mul_hi_u32 v1, v4, v1
	v_add_u32_e32 v1, v4, v1
	v_mul_hi_u32 v1, v5, v1
	v_mul_lo_u32 v3, v1, v2
	v_sub_u32_e32 v3, v5, v3
	v_add_u32_e32 v4, 1, v1
	v_cmp_ge_u32_e32 vcc, v3, v2
	s_nop 1
	v_cndmask_b32_e32 v1, v1, v4, vcc
	v_sub_u32_e32 v4, v3, v2
	v_cndmask_b32_e32 v3, v3, v4, vcc
	v_add_u32_e32 v4, 1, v1
	v_cmp_ge_u32_e32 vcc, v3, v2
	v_add_u32_e32 v3, 1, v5
	s_nop 0
	v_cndmask_b32_e32 v1, v1, v4, vcc
	v_mul_lo_u32 v4, v2, v1
	v_add_u32_e32 v2, v4, v2
	v_cmp_ne_u32_e32 vcc, v3, v2
	s_and_saveexec_b64 s[6:7], vcc
	s_xor_b64 s[6:7], exec, s[6:7]
	s_cbranch_execz .LBB0_597
	s_waitcnt lgkmcnt(0)
	v_readlane_b32 s10, v254, 39
	v_readlane_b32 s11, v254, 40
	s_nop 4
	global_load_dword v0, v193, s[10:11] sc1
	s_waitcnt vmcnt(0)
	v_cmp_eq_u32_e32 vcc, v0, v1
	s_and_saveexec_b64 s[8:9], vcc
	s_cbranch_execz .LBB0_596
	s_mov_b32 s37, 1
	s_mov_b64 s[12:13], 0
	s_branch .LBB0_587

; __device__ __forceinline__ unsigned xb_add(unsigned* p, unsigned v) { return __hip_atomic_fetch_add(p, v, __ATOMIC_RELAXED, __HIP_MEMORY_SCOPE_AGENT); }
; __device__ __forceinline__ void xcd_barrier(const XcdBarrier& b) {
;     ...
;             __builtin_amdgcn_fence(__ATOMIC_ACQUIRE, "agent");
;             xb_add(&bar[XB_XGEN(b.x)], 1u);
;             asm volatile("s_waitcnt vmcnt(0)" ::: "memory");
.LBB0_614:
	s_or_b64 exec, exec, s[8:9]
	s_mov_b64 s[8:9], exec
	v_mbcnt_lo_u32_b32 v0, s8, 0
	v_mbcnt_hi_u32_b32 v0, s9, v0
	v_cmp_eq_u32_e32 vcc, 0, v0
	s_waitcnt vmcnt(0)
	buffer_inv sc1
	s_and_saveexec_b64 s[10:11], vcc
	s_cbranch_execz .LBB0_616
	s_bcnt1_i32_b64 s8, s[8:9]
	v_mov_b32_e32 v0, s8
.LBB0_616:
	s_or_b64 exec, exec, s[10:11]
	s_waitcnt vmcnt(0)

; __device__ __forceinline__ unsigned xb_add(unsigned* p, unsigned v) { return __hip_atomic_fetch_add(p, v, __ATOMIC_RELAXED, __HIP_MEMORY_SCOPE_AGENT); }
; __device__ __forceinline__ void xcd_barrier(const XcdBarrier& b) {
;     ...
;             __builtin_amdgcn_fence(__ATOMIC_ACQUIRE, "agent");
;             xb_add(&bar[XB_XGEN(b.x)], 1u);
;             asm volatile("s_waitcnt vmcnt(0)" ::: "memory");
.LBB0_687:
	s_or_b64 exec, exec, s[6:7]
	s_mov_b64 s[6:7], exec
	v_mbcnt_lo_u32_b32 v0, s6, 0
	v_mbcnt_hi_u32_b32 v0, s7, v0
	v_cmp_eq_u32_e32 vcc, 0, v0
	s_waitcnt vmcnt(0)
	buffer_inv sc1
	s_and_saveexec_b64 s[8:9], vcc
	s_cbranch_execz .LBB0_689
	s_bcnt1_i32_b64 s6, s[6:7]
	v_mov_b32_e32 v0, s6
.LBB0_689:
	s_or_b64 exec, exec, s[8:9]
	s_waitcnt vmcnt(0)

; __device__ __forceinline__ unsigned xb_ld(unsigned* p)              { return __hip_atomic_load(p, __ATOMIC_RELAXED, __HIP_MEMORY_SCOPE_AGENT); }
; __device__ __forceinline__ unsigned xb_add(unsigned* p, unsigned v) { return __hip_atomic_fetch_add(p, v, __ATOMIC_RELAXED, __HIP_MEMORY_SCOPE_AGENT); }
; #define XB_SPIN(cond, bar) do { unsigned _sp = 0; while (cond) { __builtin_amdgcn_s_sleep(1); \
;     if ((++_sp & 255u) == 0u) { if (xb_ld(&(bar)[XB_TMO])) break; if (_sp > XB_SPIN_CAP) { atomicAdd(&(bar)[XB_TMO], 1u); break; } } } } while (0)
; __device__ __forceinline__ void xcd_barrier(const XcdBarrier& b) {
;     ...
;         const unsigned old = xb_add(&bar[XB_XSUB(b.x)], 1u);
;         const unsigned gen = old / nloc;
;         if (old + 1u == (gen + 1u) * nloc) {
;             __builtin_amdgcn_fence(__ATOMIC_RELEASE, "agent");
;             asm volatile("s_waitcnt vmcnt(0)" ::: "memory");
;             const unsigned og = xb_add(&bar[XB_TOP], 1u);
;             const unsigned tg = og / nx;
;             if (og + 1u == (tg + 1u) * nx) xb_add(&bar[XB_TOPGEN], 1u);
;             else XB_SPIN(xb_ld(&bar[XB_TOPGEN]) == tg, bar);
;             __builtin_amdgcn_fence(__ATOMIC_ACQUIRE, "agent");
;             xb_add(&bar[XB_XGEN(b.x)], 1u);
;             asm volatile("s_waitcnt vmcnt(0)" ::: "memory");
;         } else {
;             XB_SPIN(xb_ld(&bar[XB_XGEN(b.x)]) == gen, bar);
.LBB0_840:
	s_or_b64 exec, exec, s[8:9]
	v_cvt_f32_u32_e32 v4, v2
	s_waitcnt vmcnt(0)
	v_readfirstlane_b32 s6, v3
	v_sub_u32_e32 v3, 0, v2
	v_rcp_iflag_f32_e32 v4, v4
	v_add_u32_e32 v5, s6, v1
	v_mul_f32_e32 v4, 0x4f7ffffe, v4
	v_cvt_u32_f32_e32 v4, v4
	v_mul_lo_u32 v1, v3, v4
	v_mul_hi_u32 v1, v4, v1
	v_add_u32_e32 v1, v4, v1
	v_mul_hi_u32 v1, v5, v1
	v_mul_lo_u32 v3, v1, v2
	v_sub_u32_e32 v3, v5, v3
	v_add_u32_e32 v4, 1, v1
	v_cmp_ge_u32_e32 vcc, v3, v2
	s_nop 1
	v_cndmask_b32_e32 v1, v1, v4, vcc
	v_sub_u32_e32 v4, v3, v2
	v_cndmask_b32_e32 v3, v3, v4, vcc
	v_add_u32_e32 v4, 1, v1
	v_cmp_ge_u32_e32 vcc, v3, v2
	v_add_u32_e32 v3, 1, v5
	s_nop 0
	v_cndmask_b32_e32 v1, v1, v4, vcc
	v_mul_lo_u32 v4, v2, v1
	v_add_u32_e32 v2, v4, v2
	v_cmp_ne_u32_e32 vcc, v3, v2
	s_and_saveexec_b64 s[6:7], vcc
	s_xor_b64 s[6:7], exec, s[6:7]
	s_cbranch_execz .LBB0_854
	s_waitcnt lgkmcnt(0)
	v_readlane_b32 s10, v254, 39
	v_readlane_b32 s11, v254, 40
	s_nop 4
	global_load_dword v0, v193, s[10:11] sc1
	s_waitcnt vmcnt(0)
	v_cmp_eq_u32_e32 vcc, v0, v1
	s_and_saveexec_b64 s[8:9], vcc
	s_cbranch_execz .LBB0_853
	s_mov_b32 s19, 1
	s_mov_b64 s[12:13], 0
	s_branch .LBB0_844

; __device__ __forceinline__ unsigned xb_add(unsigned* p, unsigned v) { return __hip_atomic_fetch_add(p, v, __ATOMIC_RELAXED, __HIP_MEMORY_SCOPE_AGENT); }
; __device__ __forceinline__ void xcd_barrier(const XcdBarrier& b) {
;     ...
;             __builtin_amdgcn_fence(__ATOMIC_ACQUIRE, "agent");
;             xb_add(&bar[XB_XGEN(b.x)], 1u);
.LBB0_871:
	s_or_b64 exec, exec, s[8:9]
	s_mov_b64 s[8:9], exec
	v_mbcnt_lo_u32_b32 v0, s8, 0
	v_mbcnt_hi_u32_b32 v0, s9, v0
	v_cmp_eq_u32_e32 vcc, 0, v0
	s_waitcnt vmcnt(0)
	buffer_inv sc1
	s_and_saveexec_b64 s[10:11], vcc
	s_cbranch_execz .LBB0_873
	s_bcnt1_i32_b64 s8, s[8:9]
	v_mov_b32_e32 v0, s8
.LBB0_873:
	s_or_b64 exec, exec, s[10:11]
	s_waitcnt vmcnt(0)

; __device__ __forceinline__ unsigned xb_add(unsigned* p, unsigned v) { return __hip_atomic_fetch_add(p, v, __ATOMIC_RELAXED, __HIP_MEMORY_SCOPE_AGENT); }
; __device__ __forceinline__ void xcd_barrier(const XcdBarrier& b) {
;     ...
;             __builtin_amdgcn_fence(__ATOMIC_ACQUIRE, "agent");
;             xb_add(&bar[XB_XGEN(b.x)], 1u);
.LBB0_972:
	s_or_b64 exec, exec, s[8:9]
	s_mov_b64 s[8:9], exec
	v_mbcnt_lo_u32_b32 v0, s8, 0
	v_mbcnt_hi_u32_b32 v0, s9, v0
	v_cmp_eq_u32_e32 vcc, 0, v0
	s_waitcnt vmcnt(0)
	buffer_inv sc1
	s_and_saveexec_b64 s[10:11], vcc
	s_cbranch_execz .LBB0_974
	s_bcnt1_i32_b64 s3, s[8:9]
	v_mov_b32_e32 v0, s3
.LBB0_974:
	s_or_b64 exec, exec, s[10:11]
	s_waitcnt vmcnt(0)

; __device__ __forceinline__ unsigned xb_add(unsigned* p, unsigned v) { return __hip_atomic_fetch_add(p, v, __ATOMIC_RELAXED, __HIP_MEMORY_SCOPE_AGENT); }
; __device__ __forceinline__ void xcd_barrier(const XcdBarrier& b) {
;     ...
;             __builtin_amdgcn_fence(__ATOMIC_ACQUIRE, "agent");
;             xb_add(&bar[XB_XGEN(b.x)], 1u);
.LBB0_1124:
	s_or_b64 exec, exec, s[10:11]
	s_mov_b64 s[10:11], exec
	v_mbcnt_lo_u32_b32 v0, s10, 0
	v_mbcnt_hi_u32_b32 v0, s11, v0
	v_cmp_eq_u32_e32 vcc, 0, v0
	s_waitcnt vmcnt(0)
	buffer_inv sc1
	s_and_saveexec_b64 s[12:13], vcc
	s_cbranch_execz .LBB0_1126
	s_bcnt1_i32_b64 s3, s[10:11]
	v_mov_b32_e32 v0, s3
.LBB0_1126:
	s_or_b64 exec, exec, s[12:13]
	s_waitcnt vmcnt(0)

; __device__ __forceinline__ unsigned xb_add(unsigned* p, unsigned v) { return __hip_atomic_fetch_add(p, v, __ATOMIC_RELAXED, __HIP_MEMORY_SCOPE_AGENT); }
; __device__ __forceinline__ void xcd_barrier(const XcdBarrier& b) {
;     ...
;             __builtin_amdgcn_fence(__ATOMIC_ACQUIRE, "agent");
;             xb_add(&bar[XB_XGEN(b.x)], 1u);
.LBB0_1209:
	s_or_b64 exec, exec, s[10:11]
	s_mov_b64 s[10:11], exec
	v_mbcnt_lo_u32_b32 v0, s10, 0
	v_mbcnt_hi_u32_b32 v0, s11, v0
	v_cmp_eq_u32_e32 vcc, 0, v0
	s_waitcnt vmcnt(0)
	buffer_inv sc1
	s_and_saveexec_b64 s[12:13], vcc
	s_cbranch_execz .LBB0_1211
	s_bcnt1_i32_b64 s3, s[10:11]
	v_mov_b32_e32 v0, s3
.LBB0_1211:
	s_or_b64 exec, exec, s[12:13]
	s_waitcnt vmcnt(0)

; __device__ __forceinline__ unsigned xb_add(unsigned* p, unsigned v) { return __hip_atomic_fetch_add(p, v, __ATOMIC_RELAXED, __HIP_MEMORY_SCOPE_AGENT); }
; __device__ __forceinline__ void xcd_barrier(const XcdBarrier& b) {
;     ...
;             __builtin_amdgcn_fence(__ATOMIC_ACQUIRE, "agent");
;             xb_add(&bar[XB_XGEN(b.x)], 1u);
.LBB0_1321:
	s_or_b64 exec, exec, s[10:11]
	s_mov_b64 s[10:11], exec
	v_mbcnt_lo_u32_b32 v0, s10, 0
	v_mbcnt_hi_u32_b32 v0, s11, v0
	v_cmp_eq_u32_e32 vcc, 0, v0
	s_waitcnt vmcnt(0)
	buffer_inv sc1
	s_and_saveexec_b64 s[12:13], vcc
	s_cbranch_execz .LBB0_1323
	s_bcnt1_i32_b64 s3, s[10:11]
	v_mov_b32_e32 v0, s3
.LBB0_1323:
	s_or_b64 exec, exec, s[12:13]
	s_waitcnt vmcnt(0)

; __device__ __forceinline__ unsigned xb_add(unsigned* p, unsigned v) { return __hip_atomic_fetch_add(p, v, __ATOMIC_RELAXED, __HIP_MEMORY_SCOPE_AGENT); }
; __device__ __forceinline__ void xcd_barrier(const XcdBarrier& b) {
;     ...
;             __builtin_amdgcn_fence(__ATOMIC_ACQUIRE, "agent");
;             xb_add(&bar[XB_XGEN(b.x)], 1u);
.LBB0_1392:
	s_or_b64 exec, exec, s[10:11]
	s_mov_b64 s[10:11], exec
	v_mbcnt_lo_u32_b32 v0, s10, 0
	v_mbcnt_hi_u32_b32 v0, s11, v0
	v_cmp_eq_u32_e32 vcc, 0, v0
	s_waitcnt vmcnt(0)
	buffer_inv sc1
	s_and_saveexec_b64 s[12:13], vcc
	s_cbranch_execz .LBB0_1394
	s_bcnt1_i32_b64 s3, s[10:11]
	v_mov_b32_e32 v0, s3
.LBB0_1394:
	s_or_b64 exec, exec, s[12:13]
	s_waitcnt vmcnt(0)

; __device__ __forceinline__ unsigned xb_add(unsigned* p, unsigned v) { return __hip_atomic_fetch_add(p, v, __ATOMIC_RELAXED, __HIP_MEMORY_SCOPE_AGENT); }
; __device__ __forceinline__ void xcd_barrier(const XcdBarrier& b) {
;     ...
;             xb_add(&bar[XB_XGEN(b.x)], 1u);
.LBB0_1475:
	s_bcnt1_i32_b64 s3, s[10:11]
	v_mov_b32_e32 v0, s3
	s_getpc_b64 s[98:99]
